# P1 epilogue silu: the three non-transcendental steps as packed f32 ops (28 instead of 36 instructions per 8 values, same operations)
# baseline (speedup 1.0000x reference)
; #define PG8_STAGE(bufoff, gbase, voff) do { _Pragma("unroll") for (int _i = 0; _i < 2; ++_i) \
;         __builtin_amdgcn_global_load_lds((const unsigned*)((const char*)(gbase) + (voff)[_i]), (PG8_LAS unsigned*)(lds + (bufoff) + ldsw + _i * 8192), 16, 0, 0); } while (0)
; #define PG8_WAIT_V(n) asm volatile("s_waitcnt vmcnt(" #n ")" ::: "memory")
; #define PG8_BAR __builtin_amdgcn_s_barrier()
; template <class Epi, class Sched, bool ALIGN_EPI = false, bool SP2 = false, bool RS = false, bool BPRE = false>
; __device__ __forceinline__ void gemm_phase(PG8_LAS unsigned char* lds, const Gemm g, const Sched& S, const Epi& E, const float* rs_ss = nullptr, PG8_LAS float* rs_tab = nullptr) {
;     const int tid = threadIdx.x, wid = __builtin_amdgcn_readfirstlane(tid >> 6), lane = tid & 63, wr = wid >> 2, wc = wid & 3, fr = lane & 15, fq = lane >> 4;
;     const int K = g.K, nt = K / BK;
;     unsigned voffA[2], voffB[2];
; #pragma unroll
;     for (int i = 0; i < 2; ++i) { int R, C; stage_rc(tid * 16 + i * 8192, R, C); const int Rb = (Epi::PERM && !BPRE) ? ((R & ~31) + perm32(R & 31)) : R;
;         voffA[i] = (unsigned)lds_byte(R, C); voffB[i] = (unsigned)lds_byte(Rb, C); }
;     const size_t kstep = (size_t)HTB;
;     const size_t hstep = (size_t)HALF * K * 2;
;     const size_t tstep = 2 * hstep;
;     const unsigned ldsw = (unsigned)wid * 1024u;
;     const int aoff = lds_byte(wr * 64 + fr, fq * 8), boff = lds_byte(wc * 32 + fr, fq * 8);
;     ...
;     if constexpr (SP2) {
;         PG8_STAGE(PG8_SB(0, 0), cB, voffB); PG8_STAGE(PG8_SB(0, 1), cB + hstep, voffB); PG8_STAGE(PG8_SA(0, 0), cA, voffA); PG8_STAGE(PG8_SA(0, 1), cA + hstep, voffA);
;         if (wr == 1) PG8_BAR;
;         PG8_WAIT_V(2); PG8_BAR;
;         PG8_STAGE(PG8_SB(1, 0), cB + kstep, voffB); PG8_STAGE(PG8_SA(1, 0), cA + kstep, voffA); PG8_STAGE(PG8_SB(1, 1), cB + hstep + kstep, voffB);
;         PG8_WAIT_V(6); PG8_BAR;
.LBB0_190:
	s_and_b32 s5, s0, 3
	s_ashr_i32 s77, s3, 31
	s_ashr_i32 s78, s2, 31
	s_lshl_b32 s12, s7, 13
	s_lshl_b32 s13, s5, 12
	s_add_u32 s0, s58, 0x4000
	s_addc_u32 s1, s59, 0
	s_add_i32 m0, s72, 0x18000
	v_lshl_add_u64 v[4:5], s[0:1], 0, v[138:139]
	s_waitcnt vmcnt(2)
	s_barrier
	global_load_lds_dwordx4 v[4:5], off
	s_add_i32 m0, s72, 0x1a000
	v_lshl_add_u64 v[4:5], s[0:1], 0, v[140:141]
	s_add_u32 s0, s56, 0x4000
	s_addc_u32 s1, s57, 0
	s_add_i32 s79, s72, 0x8000
	global_load_lds_dwordx4 v[4:5], off
	v_lshl_add_u64 v[4:5], s[0:1], 0, v[138:139]
	s_mov_b32 m0, s79
	s_add_i32 s80, s72, 0xa000
	global_load_lds_dwordx4 v[4:5], off
	v_lshl_add_u64 v[4:5], s[0:1], 0, v[140:141]
	s_add_u32 s0, s58, 0x84000
	s_mov_b32 m0, s80
	s_addc_u32 s1, s59, 0
	global_load_lds_dwordx4 v[4:5], off
	s_add_i32 m0, s72, 0x1c000
	v_lshl_add_u64 v[4:5], s[0:1], 0, v[138:139]
	global_load_lds_dwordx4 v[4:5], off
	v_lshl_add_u64 v[4:5], s[0:1], 0, v[140:141]
	s_add_i32 m0, s72, 0x1e000
	v_and_b32_e32 v6, 48, v0
	global_load_lds_dwordx4 v[4:5], off
	v_lshlrev_b32_e32 v1, 6, v0
	s_movk_i32 s0, 0x3c0
	v_and_b32_e32 v4, 15, v0
	v_and_or_b32 v7, v1, s0, v6
	v_lshlrev_b32_e32 v1, 2, v0
	v_bfe_u32 v5, v0, 4, 2
	v_and_b32_e32 v8, 32, v1
	v_lshl_or_b32 v1, s7, 6, v4
	v_lshlrev_b32_e32 v4, 6, v4
	v_or_b32_e32 v6, v4, v6
	s_waitcnt vmcnt(6)
	s_cmpk_lt_u32 s6, 0x100
	v_lshl_or_b32 v4, v5, 4, v4
	v_cmp_eq_u32_e64 s[0:1], 0, v5
	v_bitop3_b32 v6, v6, s12, v8 bitop3:0xde
	v_bitop3_b32 v160, s13, v7, v8 bitop3:0xf6
	s_cselect_b64 s[12:13], -1, 0
	s_lshl_b32 s6, s5, 1
	v_lshl_or_b32 v4, s5, 10, v4
	v_mov_b32_e32 v5, v142
	v_add_u32_e32 v146, v2, v3
	s_add_i32 s83, 0, 0x10000
	s_add_i32 s86, 0, 0x14000
	v_mbcnt_lo_u32_b32 v2, -1, 0
	s_or_b32 s81, s6, 0xffffffa0
	v_lshl_add_u64 v[144:145], s[36:37], 0, v[4:5]
	v_mov_b32_e32 v147, v142
	v_mov_b64_e32 v[148:149], 0x700
	v_mov_b64_e32 v[150:151], 0x6ff
	s_movk_i32 s82, 0xe1
	v_add_u32_e32 v161, s83, v160
	v_add_u32_e32 v162, s86, v160
	v_add_u32_e32 v163, 0, v6
	s_mov_b32 s14, 0x3db8aa3b
	v_mov_b32_e32 v220, 0xbfb8aa3b
	v_mov_b32_e32 v221, 0xbfb8aa3b
	v_mov_b32_e32 v222, 1.0
	v_mov_b32_e32 v223, 1.0
	v_mbcnt_hi_u32_b32 v164, -1, v2
	s_barrier
	s_branch .LBB0_193

; __device__ __forceinline__ float silu_f(float x) { return x * __builtin_amdgcn_rcpf(1.0f + __builtin_amdgcn_exp2f(-x * LOG2E)); }
;     __device__ __forceinline__ void operator()(const f32x4 (&acc)[2][2][4][2], const pg8::Unit& u, int wr, int wc, int fr, int fq, const LAS float* tab) const {
;     ...
;                     f32x4 v0 = acc[ai][bj][m][0], v1 = acc[ai][bj][m][1];
;                     if (kind == 1) {
; #pragma unroll
;                         for (int e = 0; e < 4; ++e) { v0[e] = silu_f(v0[e]); v1[e] = silu_f(v1[e]); }
.LBB0_205:
	s_andn2_b64 vcc, exec, s[56:57]
	s_cbranch_vccnz .LBB0_209
	s_cmp_eq_u32 s17, 1
	s_cbranch_scc0 .LBB0_208
	v_pk_mul_f32 v[130:131], v[126:127], v[220:221]
	v_pk_mul_f32 v[134:135], v[128:129], v[220:221]
	v_pk_mul_f32 v[136:137], v[124:125], v[220:221]
	v_pk_mul_f32 v[132:133], v[122:123], v[220:221]
	v_exp_f32_e32 v130, v130
	v_exp_f32_e32 v131, v131
	v_exp_f32_e32 v134, v134
	v_exp_f32_e32 v135, v135
	v_exp_f32_e32 v136, v136
	v_exp_f32_e32 v137, v137
	v_exp_f32_e32 v132, v132
	v_exp_f32_e32 v133, v133
	v_pk_add_f32 v[130:131], v[130:131], v[222:223]
	v_pk_add_f32 v[134:135], v[134:135], v[222:223]
	v_pk_add_f32 v[136:137], v[136:137], v[222:223]
	v_pk_add_f32 v[132:133], v[132:133], v[222:223]
	v_rcp_f32_e32 v130, v130
	v_rcp_f32_e32 v131, v131
	v_rcp_f32_e32 v134, v134
	v_rcp_f32_e32 v135, v135
	v_rcp_f32_e32 v136, v136
	v_rcp_f32_e32 v137, v137
	v_rcp_f32_e32 v132, v132
	v_rcp_f32_e32 v133, v133
	v_pk_mul_f32 v[126:127], v[126:127], v[130:131]
	v_pk_mul_f32 v[128:129], v[128:129], v[134:135]
	v_pk_mul_f32 v[124:125], v[124:125], v[136:137]
	v_pk_mul_f32 v[122:123], v[122:123], v[132:133]

; __device__ __forceinline__ float silu_f(float x) { return x * __builtin_amdgcn_rcpf(1.0f + __builtin_amdgcn_exp2f(-x * LOG2E)); }
;     __device__ __forceinline__ void operator()(const f32x4 (&acc)[2][2][4][2], const pg8::Unit& u, int wr, int wc, int fr, int fq, const LAS float* tab) const {
;     ...
;                     f32x4 v0 = acc[ai][bj][m][0], v1 = acc[ai][bj][m][1];
;                     if (kind == 1) {
; #pragma unroll
;                         for (int e = 0; e < 4; ++e) { v0[e] = silu_f(v0[e]); v1[e] = silu_f(v1[e]); }
.LBB0_215:
	s_andn2_b64 vcc, exec, s[46:47]
	s_cbranch_vccnz .LBB0_219
	s_cmp_eq_u32 s17, 1
	s_cbranch_scc0 .LBB0_218
	v_pk_mul_f32 v[122:123], v[118:119], v[220:221]
	v_pk_mul_f32 v[126:127], v[120:121], v[220:221]
	v_pk_mul_f32 v[128:129], v[116:117], v[220:221]
	v_pk_mul_f32 v[124:125], v[114:115], v[220:221]
	v_exp_f32_e32 v122, v122
	v_exp_f32_e32 v123, v123
	v_exp_f32_e32 v126, v126
	v_exp_f32_e32 v127, v127
	v_exp_f32_e32 v128, v128
	v_exp_f32_e32 v129, v129
	v_exp_f32_e32 v124, v124
	v_exp_f32_e32 v125, v125
	v_pk_add_f32 v[122:123], v[122:123], v[222:223]
	v_pk_add_f32 v[126:127], v[126:127], v[222:223]
	v_pk_add_f32 v[128:129], v[128:129], v[222:223]
	v_pk_add_f32 v[124:125], v[124:125], v[222:223]
	v_rcp_f32_e32 v122, v122
	v_rcp_f32_e32 v123, v123
	v_rcp_f32_e32 v126, v126
	v_rcp_f32_e32 v127, v127
	v_rcp_f32_e32 v128, v128
	v_rcp_f32_e32 v129, v129
	v_rcp_f32_e32 v124, v124
	v_rcp_f32_e32 v125, v125
	v_pk_mul_f32 v[118:119], v[118:119], v[122:123]
	v_pk_mul_f32 v[120:121], v[120:121], v[126:127]
	v_pk_mul_f32 v[116:117], v[116:117], v[128:129]
	v_pk_mul_f32 v[114:115], v[114:115], v[124:125]

; __device__ __forceinline__ float silu_f(float x) { return x * __builtin_amdgcn_rcpf(1.0f + __builtin_amdgcn_exp2f(-x * LOG2E)); }
;     __device__ __forceinline__ void operator()(const f32x4 (&acc)[2][2][4][2], const pg8::Unit& u, int wr, int wc, int fr, int fq, const LAS float* tab) const {
;     ...
;                     f32x4 v0 = acc[ai][bj][m][0], v1 = acc[ai][bj][m][1];
;                     if (kind == 1) {
; #pragma unroll
;                         for (int e = 0; e < 4; ++e) { v0[e] = silu_f(v0[e]); v1[e] = silu_f(v1[e]); }
.LBB0_230:
	s_cmp_eq_u32 s17, 1
	s_cbranch_scc0 .LBB0_232
	s_waitcnt lgkmcnt(0)
	v_pk_mul_f32 v[114:115], v[110:111], v[220:221]
	v_pk_mul_f32 v[118:119], v[112:113], v[220:221]
	v_pk_mul_f32 v[120:121], v[108:109], v[220:221]
	v_pk_mul_f32 v[116:117], v[106:107], v[220:221]
	v_exp_f32_e32 v114, v114
	v_exp_f32_e32 v115, v115
	v_exp_f32_e32 v118, v118
	v_exp_f32_e32 v119, v119
	v_exp_f32_e32 v120, v120
	v_exp_f32_e32 v121, v121
	v_exp_f32_e32 v116, v116
	v_exp_f32_e32 v117, v117
	v_pk_add_f32 v[114:115], v[114:115], v[222:223]
	v_pk_add_f32 v[118:119], v[118:119], v[222:223]
	v_pk_add_f32 v[120:121], v[120:121], v[222:223]
	v_pk_add_f32 v[116:117], v[116:117], v[222:223]
	v_rcp_f32_e32 v114, v114
	v_rcp_f32_e32 v115, v115
	v_rcp_f32_e32 v118, v118
	v_rcp_f32_e32 v119, v119
	v_rcp_f32_e32 v120, v120
	v_rcp_f32_e32 v121, v121
	v_rcp_f32_e32 v116, v116
	v_rcp_f32_e32 v117, v117
	v_pk_mul_f32 v[110:111], v[110:111], v[114:115]
	v_pk_mul_f32 v[112:113], v[112:113], v[118:119]
	v_pk_mul_f32 v[108:109], v[108:109], v[120:121]
	v_pk_mul_f32 v[106:107], v[106:107], v[116:117]

; __device__ __forceinline__ float silu_f(float x) { return x * __builtin_amdgcn_rcpf(1.0f + __builtin_amdgcn_exp2f(-x * LOG2E)); }
;     __device__ __forceinline__ void operator()(const f32x4 (&acc)[2][2][4][2], const pg8::Unit& u, int wr, int wc, int fr, int fq, const LAS float* tab) const {
;     ...
;                     f32x4 v0 = acc[ai][bj][m][0], v1 = acc[ai][bj][m][1];
;                     if (kind == 1) {
; #pragma unroll
;                         for (int e = 0; e < 4; ++e) { v0[e] = silu_f(v0[e]); v1[e] = silu_f(v1[e]); }
.LBB0_239:
	s_andn2_b64 vcc, exec, s[4:5]
	s_cbranch_vccnz .LBB0_243
	s_cmp_eq_u32 s17, 1
	s_cbranch_scc0 .LBB0_242
	v_pk_mul_f32 v[106:107], v[102:103], v[220:221]
	v_pk_mul_f32 v[110:111], v[104:105], v[220:221]
	v_pk_mul_f32 v[112:113], v[100:101], v[220:221]
	v_pk_mul_f32 v[108:109], v[98:99], v[220:221]
	v_exp_f32_e32 v106, v106
	v_exp_f32_e32 v107, v107
	v_exp_f32_e32 v110, v110
	v_exp_f32_e32 v111, v111
	v_exp_f32_e32 v112, v112
	v_exp_f32_e32 v113, v113
	v_exp_f32_e32 v108, v108
	v_exp_f32_e32 v109, v109
	v_pk_add_f32 v[106:107], v[106:107], v[222:223]
	v_pk_add_f32 v[110:111], v[110:111], v[222:223]
	v_pk_add_f32 v[112:113], v[112:113], v[222:223]
	v_pk_add_f32 v[108:109], v[108:109], v[222:223]
	v_rcp_f32_e32 v106, v106
	v_rcp_f32_e32 v107, v107
	v_rcp_f32_e32 v110, v110
	v_rcp_f32_e32 v111, v111
	v_rcp_f32_e32 v112, v112
	v_rcp_f32_e32 v113, v113
	v_rcp_f32_e32 v108, v108
	v_rcp_f32_e32 v109, v109
	v_pk_mul_f32 v[102:103], v[102:103], v[106:107]
	v_pk_mul_f32 v[104:105], v[104:105], v[110:111]
	v_pk_mul_f32 v[100:101], v[100:101], v[112:113]
	v_pk_mul_f32 v[98:99], v[98:99], v[108:109]

; __device__ __forceinline__ float silu_f(float x) { return x * __builtin_amdgcn_rcpf(1.0f + __builtin_amdgcn_exp2f(-x * LOG2E)); }
;     __device__ __forceinline__ void operator()(const f32x4 (&acc)[2][2][4][2], const pg8::Unit& u, int wr, int wc, int fr, int fq, const LAS float* tab) const {
;     ...
;                     f32x4 v0 = acc[ai][bj][m][0], v1 = acc[ai][bj][m][1];
;                     if (kind == 1) {
; #pragma unroll
;                         for (int e = 0; e < 4; ++e) { v0[e] = silu_f(v0[e]); v1[e] = silu_f(v1[e]); }
.LBB0_254:
	s_cmp_eq_u32 s17, 1
	s_cbranch_scc0 .LBB0_256
	s_waitcnt lgkmcnt(0)
	v_pk_mul_f32 v[98:99], v[94:95], v[220:221]
	v_pk_mul_f32 v[102:103], v[96:97], v[220:221]
	v_pk_mul_f32 v[104:105], v[92:93], v[220:221]
	v_pk_mul_f32 v[100:101], v[90:91], v[220:221]
	v_exp_f32_e32 v98, v98
	v_exp_f32_e32 v99, v99
	v_exp_f32_e32 v102, v102
	v_exp_f32_e32 v103, v103
	v_exp_f32_e32 v104, v104
	v_exp_f32_e32 v105, v105
	v_exp_f32_e32 v100, v100
	v_exp_f32_e32 v101, v101
	v_pk_add_f32 v[98:99], v[98:99], v[222:223]
	v_pk_add_f32 v[102:103], v[102:103], v[222:223]
	v_pk_add_f32 v[104:105], v[104:105], v[222:223]
	v_pk_add_f32 v[100:101], v[100:101], v[222:223]
	v_rcp_f32_e32 v98, v98
	v_rcp_f32_e32 v99, v99
	v_rcp_f32_e32 v102, v102
	v_rcp_f32_e32 v103, v103
	v_rcp_f32_e32 v104, v104
	v_rcp_f32_e32 v105, v105
	v_rcp_f32_e32 v100, v100
	v_rcp_f32_e32 v101, v101
	v_pk_mul_f32 v[94:95], v[94:95], v[98:99]
	v_pk_mul_f32 v[96:97], v[96:97], v[102:103]
	v_pk_mul_f32 v[92:93], v[92:93], v[104:105]
	v_pk_mul_f32 v[90:91], v[90:91], v[100:101]

; __device__ __forceinline__ float silu_f(float x) { return x * __builtin_amdgcn_rcpf(1.0f + __builtin_amdgcn_exp2f(-x * LOG2E)); }
;     __device__ __forceinline__ void operator()(const f32x4 (&acc)[2][2][4][2], const pg8::Unit& u, int wr, int wc, int fr, int fq, const LAS float* tab) const {
;     ...
;                     f32x4 v0 = acc[ai][bj][m][0], v1 = acc[ai][bj][m][1];
;                     if (kind == 1) {
; #pragma unroll
;                         for (int e = 0; e < 4; ++e) { v0[e] = silu_f(v0[e]); v1[e] = silu_f(v1[e]); }
.LBB0_263:
	s_andn2_b64 vcc, exec, s[56:57]
	s_cbranch_vccnz .LBB0_267
	s_cmp_eq_u32 s17, 1
	s_cbranch_scc0 .LBB0_266
	v_pk_mul_f32 v[90:91], v[86:87], v[220:221]
	v_pk_mul_f32 v[94:95], v[88:89], v[220:221]
	v_pk_mul_f32 v[96:97], v[84:85], v[220:221]
	v_pk_mul_f32 v[92:93], v[82:83], v[220:221]
	v_exp_f32_e32 v90, v90
	v_exp_f32_e32 v91, v91
	v_exp_f32_e32 v94, v94
	v_exp_f32_e32 v95, v95
	v_exp_f32_e32 v96, v96
	v_exp_f32_e32 v97, v97
	v_exp_f32_e32 v92, v92
	v_exp_f32_e32 v93, v93
	v_pk_add_f32 v[90:91], v[90:91], v[222:223]
	v_pk_add_f32 v[94:95], v[94:95], v[222:223]
	v_pk_add_f32 v[96:97], v[96:97], v[222:223]
	v_pk_add_f32 v[92:93], v[92:93], v[222:223]
	v_rcp_f32_e32 v90, v90
	v_rcp_f32_e32 v91, v91
	v_rcp_f32_e32 v94, v94
	v_rcp_f32_e32 v95, v95
	v_rcp_f32_e32 v96, v96
	v_rcp_f32_e32 v97, v97
	v_rcp_f32_e32 v92, v92
	v_rcp_f32_e32 v93, v93
	v_pk_mul_f32 v[86:87], v[86:87], v[90:91]
	v_pk_mul_f32 v[88:89], v[88:89], v[94:95]
	v_pk_mul_f32 v[84:85], v[84:85], v[96:97]
	v_pk_mul_f32 v[82:83], v[82:83], v[92:93]

; __device__ __forceinline__ float silu_f(float x) { return x * __builtin_amdgcn_rcpf(1.0f + __builtin_amdgcn_exp2f(-x * LOG2E)); }
;     __device__ __forceinline__ void operator()(const f32x4 (&acc)[2][2][4][2], const pg8::Unit& u, int wr, int wc, int fr, int fq, const LAS float* tab) const {
;     ...
;                     f32x4 v0 = acc[ai][bj][m][0], v1 = acc[ai][bj][m][1];
;                     if (kind == 1) {
; #pragma unroll
;                         for (int e = 0; e < 4; ++e) { v0[e] = silu_f(v0[e]); v1[e] = silu_f(v1[e]); }
.LBB0_278:
	s_cmp_eq_u32 s17, 1
	s_cbranch_scc0 .LBB0_280
	s_waitcnt lgkmcnt(0)
	v_pk_mul_f32 v[82:83], v[78:79], v[220:221]
	v_pk_mul_f32 v[86:87], v[80:81], v[220:221]
	v_pk_mul_f32 v[88:89], v[76:77], v[220:221]
	v_pk_mul_f32 v[84:85], v[74:75], v[220:221]
	v_exp_f32_e32 v82, v82
	v_exp_f32_e32 v83, v83
	v_exp_f32_e32 v86, v86
	v_exp_f32_e32 v87, v87
	v_exp_f32_e32 v88, v88
	v_exp_f32_e32 v89, v89
	v_exp_f32_e32 v84, v84
	v_exp_f32_e32 v85, v85
	v_pk_add_f32 v[82:83], v[82:83], v[222:223]
	v_pk_add_f32 v[86:87], v[86:87], v[222:223]
	v_pk_add_f32 v[88:89], v[88:89], v[222:223]
	v_pk_add_f32 v[84:85], v[84:85], v[222:223]
	v_rcp_f32_e32 v82, v82
	v_rcp_f32_e32 v83, v83
	v_rcp_f32_e32 v86, v86
	v_rcp_f32_e32 v87, v87
	v_rcp_f32_e32 v88, v88
	v_rcp_f32_e32 v89, v89
	v_rcp_f32_e32 v84, v84
	v_rcp_f32_e32 v85, v85
	v_pk_mul_f32 v[78:79], v[78:79], v[82:83]
	v_pk_mul_f32 v[80:81], v[80:81], v[86:87]
	v_pk_mul_f32 v[76:77], v[76:77], v[88:89]
	v_pk_mul_f32 v[74:75], v[74:75], v[84:85]

; __device__ __forceinline__ float silu_f(float x) { return x * __builtin_amdgcn_rcpf(1.0f + __builtin_amdgcn_exp2f(-x * LOG2E)); }
;     __device__ __forceinline__ void operator()(const f32x4 (&acc)[2][2][4][2], const pg8::Unit& u, int wr, int wc, int fr, int fq, const LAS float* tab) const {
;     ...
;                     f32x4 v0 = acc[ai][bj][m][0], v1 = acc[ai][bj][m][1];
;                     if (kind == 1) {
; #pragma unroll
;                         for (int e = 0; e < 4; ++e) { v0[e] = silu_f(v0[e]); v1[e] = silu_f(v1[e]); }
.LBB0_287:
	s_andn2_b64 vcc, exec, s[56:57]
	s_cbranch_vccnz .LBB0_291
	s_cmp_eq_u32 s17, 1
	s_cbranch_scc0 .LBB0_290
	v_pk_mul_f32 v[74:75], v[70:71], v[220:221]
	v_pk_mul_f32 v[78:79], v[72:73], v[220:221]
	v_pk_mul_f32 v[80:81], v[68:69], v[220:221]
	v_pk_mul_f32 v[76:77], v[66:67], v[220:221]
	v_exp_f32_e32 v74, v74
	v_exp_f32_e32 v75, v75
	v_exp_f32_e32 v78, v78
	v_exp_f32_e32 v79, v79
	v_exp_f32_e32 v80, v80
	v_exp_f32_e32 v81, v81
	v_exp_f32_e32 v76, v76
	v_exp_f32_e32 v77, v77
	v_pk_add_f32 v[74:75], v[74:75], v[222:223]
	v_pk_add_f32 v[78:79], v[78:79], v[222:223]
	v_pk_add_f32 v[80:81], v[80:81], v[222:223]
	v_pk_add_f32 v[76:77], v[76:77], v[222:223]
	v_rcp_f32_e32 v74, v74
	v_rcp_f32_e32 v75, v75
	v_rcp_f32_e32 v78, v78
	v_rcp_f32_e32 v79, v79
	v_rcp_f32_e32 v80, v80
	v_rcp_f32_e32 v81, v81
	v_rcp_f32_e32 v76, v76
	v_rcp_f32_e32 v77, v77
	v_pk_mul_f32 v[70:71], v[70:71], v[74:75]
	v_pk_mul_f32 v[72:73], v[72:73], v[78:79]
	v_pk_mul_f32 v[68:69], v[68:69], v[80:81]
	v_pk_mul_f32 v[66:67], v[66:67], v[76:77]

; __device__ __forceinline__ float silu_f(float x) { return x * __builtin_amdgcn_rcpf(1.0f + __builtin_amdgcn_exp2f(-x * LOG2E)); }
;     __device__ __forceinline__ void operator()(const f32x4 (&acc)[2][2][4][2], const pg8::Unit& u, int wr, int wc, int fr, int fq, const LAS float* tab) const {
;     ...
;                     f32x4 v0 = acc[ai][bj][m][0], v1 = acc[ai][bj][m][1];
;                     if (kind == 1) {
; #pragma unroll
;                         for (int e = 0; e < 4; ++e) { v0[e] = silu_f(v0[e]); v1[e] = silu_f(v1[e]); }
.LBB0_302:
	s_cmp_eq_u32 s17, 1
	s_cbranch_scc0 .LBB0_304
	s_waitcnt lgkmcnt(0)
	v_pk_mul_f32 v[66:67], v[62:63], v[220:221]
	v_pk_mul_f32 v[70:71], v[64:65], v[220:221]
	v_pk_mul_f32 v[72:73], v[60:61], v[220:221]
	v_pk_mul_f32 v[68:69], v[58:59], v[220:221]
	v_exp_f32_e32 v66, v66
	v_exp_f32_e32 v67, v67
	v_exp_f32_e32 v70, v70
	v_exp_f32_e32 v71, v71
	v_exp_f32_e32 v72, v72
	v_exp_f32_e32 v73, v73
	v_exp_f32_e32 v68, v68
	v_exp_f32_e32 v69, v69
	v_pk_add_f32 v[66:67], v[66:67], v[222:223]
	v_pk_add_f32 v[70:71], v[70:71], v[222:223]
	v_pk_add_f32 v[72:73], v[72:73], v[222:223]
	v_pk_add_f32 v[68:69], v[68:69], v[222:223]
	v_rcp_f32_e32 v66, v66
	v_rcp_f32_e32 v67, v67
	v_rcp_f32_e32 v70, v70
	v_rcp_f32_e32 v71, v71
	v_rcp_f32_e32 v72, v72
	v_rcp_f32_e32 v73, v73
	v_rcp_f32_e32 v68, v68
	v_rcp_f32_e32 v69, v69
	v_pk_mul_f32 v[62:63], v[62:63], v[66:67]
	v_pk_mul_f32 v[64:65], v[64:65], v[70:71]
	v_pk_mul_f32 v[60:61], v[60:61], v[72:73]
	v_pk_mul_f32 v[58:59], v[58:59], v[68:69]

; __device__ __forceinline__ float silu_f(float x) { return x * __builtin_amdgcn_rcpf(1.0f + __builtin_amdgcn_exp2f(-x * LOG2E)); }
;     __device__ __forceinline__ void operator()(const f32x4 (&acc)[2][2][4][2], const pg8::Unit& u, int wr, int wc, int fr, int fq, const LAS float* tab) const {
;     ...
;                     f32x4 v0 = acc[ai][bj][m][0], v1 = acc[ai][bj][m][1];
;                     if (kind == 1) {
; #pragma unroll
;                         for (int e = 0; e < 4; ++e) { v0[e] = silu_f(v0[e]); v1[e] = silu_f(v1[e]); }
.LBB0_311:
	s_andn2_b64 vcc, exec, s[56:57]
	s_cbranch_vccnz .LBB0_315
	s_cmp_eq_u32 s17, 1
	s_cbranch_scc0 .LBB0_314
	v_pk_mul_f32 v[58:59], v[54:55], v[220:221]
	v_pk_mul_f32 v[62:63], v[56:57], v[220:221]
	v_pk_mul_f32 v[64:65], v[52:53], v[220:221]
	v_pk_mul_f32 v[60:61], v[50:51], v[220:221]
	v_exp_f32_e32 v58, v58
	v_exp_f32_e32 v59, v59
	v_exp_f32_e32 v62, v62
	v_exp_f32_e32 v63, v63
	v_exp_f32_e32 v64, v64
	v_exp_f32_e32 v65, v65
	v_exp_f32_e32 v60, v60
	v_exp_f32_e32 v61, v61
	v_pk_add_f32 v[58:59], v[58:59], v[222:223]
	v_pk_add_f32 v[62:63], v[62:63], v[222:223]
	v_pk_add_f32 v[64:65], v[64:65], v[222:223]
	v_pk_add_f32 v[60:61], v[60:61], v[222:223]
	v_rcp_f32_e32 v58, v58
	v_rcp_f32_e32 v59, v59
	v_rcp_f32_e32 v62, v62
	v_rcp_f32_e32 v63, v63
	v_rcp_f32_e32 v64, v64
	v_rcp_f32_e32 v65, v65
	v_rcp_f32_e32 v60, v60
	v_rcp_f32_e32 v61, v61
	v_pk_mul_f32 v[54:55], v[54:55], v[58:59]
	v_pk_mul_f32 v[56:57], v[56:57], v[62:63]
	v_pk_mul_f32 v[52:53], v[52:53], v[64:65]
	v_pk_mul_f32 v[50:51], v[50:51], v[60:61]

; __device__ __forceinline__ float silu_f(float x) { return x * __builtin_amdgcn_rcpf(1.0f + __builtin_amdgcn_exp2f(-x * LOG2E)); }
;     __device__ __forceinline__ void operator()(const f32x4 (&acc)[2][2][4][2], const pg8::Unit& u, int wr, int wc, int fr, int fq, const LAS float* tab) const {
;     ...
;                     f32x4 v0 = acc[ai][bj][m][0], v1 = acc[ai][bj][m][1];
;                     if (kind == 1) {
; #pragma unroll
;                         for (int e = 0; e < 4; ++e) { v0[e] = silu_f(v0[e]); v1[e] = silu_f(v1[e]); }
.LBB0_326:
	s_cmp_eq_u32 s17, 1
	s_cbranch_scc0 .LBB0_328
	s_waitcnt lgkmcnt(0)
	v_pk_mul_f32 v[50:51], v[46:47], v[220:221]
	v_pk_mul_f32 v[54:55], v[48:49], v[220:221]
	v_pk_mul_f32 v[56:57], v[44:45], v[220:221]
	v_pk_mul_f32 v[52:53], v[42:43], v[220:221]
	v_exp_f32_e32 v50, v50
	v_exp_f32_e32 v51, v51
	v_exp_f32_e32 v54, v54
	v_exp_f32_e32 v55, v55
	v_exp_f32_e32 v56, v56
	v_exp_f32_e32 v57, v57
	v_exp_f32_e32 v52, v52
	v_exp_f32_e32 v53, v53
	v_pk_add_f32 v[50:51], v[50:51], v[222:223]
	v_pk_add_f32 v[54:55], v[54:55], v[222:223]
	v_pk_add_f32 v[56:57], v[56:57], v[222:223]
	v_pk_add_f32 v[52:53], v[52:53], v[222:223]
	v_rcp_f32_e32 v50, v50
	v_rcp_f32_e32 v51, v51
	v_rcp_f32_e32 v54, v54
	v_rcp_f32_e32 v55, v55
	v_rcp_f32_e32 v56, v56
	v_rcp_f32_e32 v57, v57
	v_rcp_f32_e32 v52, v52
	v_rcp_f32_e32 v53, v53
	v_pk_mul_f32 v[46:47], v[46:47], v[50:51]
	v_pk_mul_f32 v[48:49], v[48:49], v[54:55]
	v_pk_mul_f32 v[44:45], v[44:45], v[56:57]
	v_pk_mul_f32 v[42:43], v[42:43], v[52:53]

; __device__ __forceinline__ float silu_f(float x) { return x * __builtin_amdgcn_rcpf(1.0f + __builtin_amdgcn_exp2f(-x * LOG2E)); }
;     __device__ __forceinline__ void operator()(const f32x4 (&acc)[2][2][4][2], const pg8::Unit& u, int wr, int wc, int fr, int fq, const LAS float* tab) const {
;     ...
;                     f32x4 v0 = acc[ai][bj][m][0], v1 = acc[ai][bj][m][1];
;                     if (kind == 1) {
; #pragma unroll
;                         for (int e = 0; e < 4; ++e) { v0[e] = silu_f(v0[e]); v1[e] = silu_f(v1[e]); }
.LBB0_335:
	s_andn2_b64 vcc, exec, s[56:57]
	s_cbranch_vccnz .LBB0_339
	s_cmp_eq_u32 s17, 1
	s_cbranch_scc0 .LBB0_338
	v_pk_mul_f32 v[42:43], v[38:39], v[220:221]
	v_pk_mul_f32 v[46:47], v[40:41], v[220:221]
	v_pk_mul_f32 v[48:49], v[36:37], v[220:221]
	v_pk_mul_f32 v[44:45], v[34:35], v[220:221]
	v_exp_f32_e32 v42, v42
	v_exp_f32_e32 v43, v43
	v_exp_f32_e32 v46, v46
	v_exp_f32_e32 v47, v47
	v_exp_f32_e32 v48, v48
	v_exp_f32_e32 v49, v49
	v_exp_f32_e32 v44, v44
	v_exp_f32_e32 v45, v45
	v_pk_add_f32 v[42:43], v[42:43], v[222:223]
	v_pk_add_f32 v[46:47], v[46:47], v[222:223]
	v_pk_add_f32 v[48:49], v[48:49], v[222:223]
	v_pk_add_f32 v[44:45], v[44:45], v[222:223]
	v_rcp_f32_e32 v42, v42
	v_rcp_f32_e32 v43, v43
	v_rcp_f32_e32 v46, v46
	v_rcp_f32_e32 v47, v47
	v_rcp_f32_e32 v48, v48
	v_rcp_f32_e32 v49, v49
	v_rcp_f32_e32 v44, v44
	v_rcp_f32_e32 v45, v45
	v_pk_mul_f32 v[38:39], v[38:39], v[42:43]
	v_pk_mul_f32 v[40:41], v[40:41], v[46:47]
	v_pk_mul_f32 v[36:37], v[36:37], v[48:49]
	v_pk_mul_f32 v[34:35], v[34:35], v[44:45]

; __device__ __forceinline__ float silu_f(float x) { return x * __builtin_amdgcn_rcpf(1.0f + __builtin_amdgcn_exp2f(-x * LOG2E)); }
;     __device__ __forceinline__ void operator()(const f32x4 (&acc)[2][2][4][2], const pg8::Unit& u, int wr, int wc, int fr, int fq, const LAS float* tab) const {
;     ...
;                     f32x4 v0 = acc[ai][bj][m][0], v1 = acc[ai][bj][m][1];
;                     if (kind == 1) {
; #pragma unroll
;                         for (int e = 0; e < 4; ++e) { v0[e] = silu_f(v0[e]); v1[e] = silu_f(v1[e]); }
.LBB0_350:
	s_cmp_eq_u32 s17, 1
	s_cbranch_scc0 .LBB0_352
	s_waitcnt lgkmcnt(0)
	v_pk_mul_f32 v[34:35], v[30:31], v[220:221]
	v_pk_mul_f32 v[38:39], v[32:33], v[220:221]
	v_pk_mul_f32 v[40:41], v[28:29], v[220:221]
	v_pk_mul_f32 v[36:37], v[26:27], v[220:221]
	v_exp_f32_e32 v34, v34
	v_exp_f32_e32 v35, v35
	v_exp_f32_e32 v38, v38
	v_exp_f32_e32 v39, v39
	v_exp_f32_e32 v40, v40
	v_exp_f32_e32 v41, v41
	v_exp_f32_e32 v36, v36
	v_exp_f32_e32 v37, v37
	v_pk_add_f32 v[34:35], v[34:35], v[222:223]
	v_pk_add_f32 v[38:39], v[38:39], v[222:223]
	v_pk_add_f32 v[40:41], v[40:41], v[222:223]
	v_pk_add_f32 v[36:37], v[36:37], v[222:223]
	v_rcp_f32_e32 v34, v34
	v_rcp_f32_e32 v35, v35
	v_rcp_f32_e32 v38, v38
	v_rcp_f32_e32 v39, v39
	v_rcp_f32_e32 v40, v40
	v_rcp_f32_e32 v41, v41
	v_rcp_f32_e32 v36, v36
	v_rcp_f32_e32 v37, v37
	v_pk_mul_f32 v[30:31], v[30:31], v[34:35]
	v_pk_mul_f32 v[32:33], v[32:33], v[38:39]
	v_pk_mul_f32 v[28:29], v[28:29], v[40:41]
	v_pk_mul_f32 v[26:27], v[26:27], v[36:37]

; __device__ __forceinline__ float silu_f(float x) { return x * __builtin_amdgcn_rcpf(1.0f + __builtin_amdgcn_exp2f(-x * LOG2E)); }
;     __device__ __forceinline__ void operator()(const f32x4 (&acc)[2][2][4][2], const pg8::Unit& u, int wr, int wc, int fr, int fq, const LAS float* tab) const {
;     ...
;                     f32x4 v0 = acc[ai][bj][m][0], v1 = acc[ai][bj][m][1];
;                     if (kind == 1) {
; #pragma unroll
;                         for (int e = 0; e < 4; ++e) { v0[e] = silu_f(v0[e]); v1[e] = silu_f(v1[e]); }
.LBB0_359:
	s_andn2_b64 vcc, exec, s[56:57]
	s_cbranch_vccnz .LBB0_363
	s_cmp_eq_u32 s17, 1
	s_cbranch_scc0 .LBB0_362
	v_pk_mul_f32 v[26:27], v[22:23], v[220:221]
	v_pk_mul_f32 v[30:31], v[24:25], v[220:221]
	v_pk_mul_f32 v[32:33], v[20:21], v[220:221]
	v_pk_mul_f32 v[28:29], v[18:19], v[220:221]
	v_exp_f32_e32 v26, v26
	v_exp_f32_e32 v27, v27
	v_exp_f32_e32 v30, v30
	v_exp_f32_e32 v31, v31
	v_exp_f32_e32 v32, v32
	v_exp_f32_e32 v33, v33
	v_exp_f32_e32 v28, v28
	v_exp_f32_e32 v29, v29
	v_pk_add_f32 v[26:27], v[26:27], v[222:223]
	v_pk_add_f32 v[30:31], v[30:31], v[222:223]
	v_pk_add_f32 v[32:33], v[32:33], v[222:223]
	v_pk_add_f32 v[28:29], v[28:29], v[222:223]
	v_rcp_f32_e32 v26, v26
	v_rcp_f32_e32 v27, v27
	v_rcp_f32_e32 v30, v30
	v_rcp_f32_e32 v31, v31
	v_rcp_f32_e32 v32, v32
	v_rcp_f32_e32 v33, v33
	v_rcp_f32_e32 v28, v28
	v_rcp_f32_e32 v29, v29
	v_pk_mul_f32 v[22:23], v[22:23], v[26:27]
	v_pk_mul_f32 v[24:25], v[24:25], v[30:31]
	v_pk_mul_f32 v[20:21], v[20:21], v[32:33]
	v_pk_mul_f32 v[18:19], v[18:19], v[28:29]

; __device__ __forceinline__ float silu_f(float x) { return x * __builtin_amdgcn_rcpf(1.0f + __builtin_amdgcn_exp2f(-x * LOG2E)); }
;     __device__ __forceinline__ void operator()(const f32x4 (&acc)[2][2][4][2], const pg8::Unit& u, int wr, int wc, int fr, int fq, const LAS float* tab) const {
;     ...
;                     f32x4 v0 = acc[ai][bj][m][0], v1 = acc[ai][bj][m][1];
;                     if (kind == 1) {
; #pragma unroll
;                         for (int e = 0; e < 4; ++e) { v0[e] = silu_f(v0[e]); v1[e] = silu_f(v1[e]); }
.LBB0_374:
	s_cmp_eq_u32 s17, 1
	s_cbranch_scc0 .LBB0_376
	s_waitcnt lgkmcnt(0)
	v_pk_mul_f32 v[18:19], v[14:15], v[220:221]
	v_pk_mul_f32 v[22:23], v[16:17], v[220:221]
	v_pk_mul_f32 v[24:25], v[12:13], v[220:221]
	v_pk_mul_f32 v[20:21], v[10:11], v[220:221]
	v_exp_f32_e32 v18, v18
	v_exp_f32_e32 v19, v19
	v_exp_f32_e32 v22, v22
	v_exp_f32_e32 v23, v23
	v_exp_f32_e32 v24, v24
	v_exp_f32_e32 v25, v25
	v_exp_f32_e32 v20, v20
	v_exp_f32_e32 v21, v21
	v_pk_add_f32 v[18:19], v[18:19], v[222:223]
	v_pk_add_f32 v[22:23], v[22:23], v[222:223]
	v_pk_add_f32 v[24:25], v[24:25], v[222:223]
	v_pk_add_f32 v[20:21], v[20:21], v[222:223]
	v_rcp_f32_e32 v18, v18
	v_rcp_f32_e32 v19, v19
	v_rcp_f32_e32 v22, v22
	v_rcp_f32_e32 v23, v23
	v_rcp_f32_e32 v24, v24
	v_rcp_f32_e32 v25, v25
	v_rcp_f32_e32 v20, v20
	v_rcp_f32_e32 v21, v21
	v_pk_mul_f32 v[14:15], v[14:15], v[18:19]
	v_pk_mul_f32 v[16:17], v[16:17], v[22:23]
	v_pk_mul_f32 v[12:13], v[12:13], v[24:25]
	v_pk_mul_f32 v[10:11], v[10:11], v[20:21]

; __device__ __forceinline__ float silu_f(float x) { return x * __builtin_amdgcn_rcpf(1.0f + __builtin_amdgcn_exp2f(-x * LOG2E)); }
;     __device__ __forceinline__ void operator()(const f32x4 (&acc)[2][2][4][2], const pg8::Unit& u, int wr, int wc, int fr, int fq, const LAS float* tab) const {
;     ...
;                     f32x4 v0 = acc[ai][bj][m][0], v1 = acc[ai][bj][m][1];
;                     if (kind == 1) {
; #pragma unroll
;                         for (int e = 0; e < 4; ++e) { v0[e] = silu_f(v0[e]); v1[e] = silu_f(v1[e]); }
.LBB0_383:
	s_andn2_b64 vcc, exec, s[56:57]
	s_cbranch_vccnz .LBB0_387
	s_cmp_eq_u32 s17, 1
	s_cbranch_scc0 .LBB0_386
	v_pk_mul_f32 v[10:11], v[6:7], v[220:221]
	v_pk_mul_f32 v[14:15], v[8:9], v[220:221]
	v_pk_mul_f32 v[16:17], v[4:5], v[220:221]
	v_pk_mul_f32 v[12:13], v[2:3], v[220:221]
	v_exp_f32_e32 v10, v10
	v_exp_f32_e32 v11, v11
	v_exp_f32_e32 v14, v14
	v_exp_f32_e32 v15, v15
	v_exp_f32_e32 v16, v16
	v_exp_f32_e32 v17, v17
	v_exp_f32_e32 v12, v12
	v_exp_f32_e32 v13, v13
	v_pk_add_f32 v[10:11], v[10:11], v[222:223]
	v_pk_add_f32 v[14:15], v[14:15], v[222:223]
	v_pk_add_f32 v[16:17], v[16:17], v[222:223]
	v_pk_add_f32 v[12:13], v[12:13], v[222:223]
	v_rcp_f32_e32 v10, v10
	v_rcp_f32_e32 v11, v11
	v_rcp_f32_e32 v14, v14
	v_rcp_f32_e32 v15, v15
	v_rcp_f32_e32 v16, v16
	v_rcp_f32_e32 v17, v17
	v_rcp_f32_e32 v12, v12
	v_rcp_f32_e32 v13, v13
	v_pk_mul_f32 v[6:7], v[6:7], v[10:11]
	v_pk_mul_f32 v[8:9], v[8:9], v[14:15]
	v_pk_mul_f32 v[4:5], v[4:5], v[16:17]
	v_pk_mul_f32 v[2:3], v[2:3], v[12:13]
